# gate/up GEMM epilogues: the row sum-of-squares for the next unit is prefetched during the current epilogue (spare registers), the epilogue's vmcnt(0) wait removed
# baseline (speedup 1.0000x reference)
.LBB0_775:
	s_or_b64 exec, exec, s[4:5]
	s_mov_b64 s[4:5], s[0:1]
	s_mov_b32 s42, s2
	s_waitcnt lgkmcnt(0)
	s_barrier
	v_mbcnt_lo_u32_b32 v8, -1, 0
	v_mbcnt_hi_u32_b32 v8, -1, v8
	s_cmpk_gt_i32 s42, 0xaff
	v_add_u32_e32 v0, s33, v8
	s_nop 0
	v_readfirstlane_b32 s18, v0
	s_cbranch_scc1 .LBB0_791
	v_lshlrev_b32_e32 v1, 4, v0
	v_add_u32_e32 v2, 0x2000, v1
	v_ashrrev_i32_e32 v3, 31, v2
	v_lshrrev_b32_e32 v3, 22, v3
	v_add_u32_e32 v3, v2, v3
	v_ashrrev_i32_e32 v9, 10, v3
	v_mul_i32_i24_e32 v3, 0x400, v9
	v_sub_u32_e32 v2, v2, v3
	v_lshrrev_b32_e32 v3, 4, v2
	v_bitop3_b32 v2, v3, v2, 32 bitop3:0x6c
	v_ashrrev_i32_e32 v3, 31, v2
	v_lshrrev_b32_e32 v3, 26, v3
	v_add_u32_e32 v3, v2, v3
	v_lshlrev_b32_e32 v4, 3, v9
	v_ashrrev_i32_e32 v10, 6, v3
	v_and_b32_e32 v4, -16, v4
	v_add_u32_e32 v4, v10, v4
	v_and_b32_e32 v5, 3, v10
	s_mov_b32 s6, 0x1fffe0
	v_lshrrev_b32_e32 v6, 2, v4
	v_lshlrev_b32_e32 v7, 1, v4
	v_and_b32_e32 v3, 0xc0, v3
	v_and_or_b32 v5, v4, s6, v5
	v_and_b32_e32 v6, 4, v6
	v_and_b32_e32 v7, 24, v7
	v_sub_u32_e32 v2, v2, v3
	v_mov_b32_e32 v3, 1
	v_or3_b32 v5, v5, v6, v7
	v_lshlrev_b32_e32 v6, 5, v9
	v_ashrrev_i16_sdwa v2, v3, sext(v2) dst_sel:DWORD dst_unused:UNUSED_PAD src0_sel:DWORD src1_sel:BYTE_0
	v_and_b32_e32 v6, 32, v6
	v_bfe_i32 v11, v2, 0, 16
	v_add_lshl_u32 v2, v6, v11, 1
	v_lshl_add_u32 v128, v5, 11, v2
	v_lshl_add_u32 v130, v4, 11, v2
	v_bfe_i32 v2, v0, 27, 1
	v_lshrrev_b32_e32 v2, 22, v2
	v_add_u32_e32 v2, v1, v2
	s_load_dwordx2 s[4:5], s[4:5], 0xa0
	v_and_b32_e32 v2, 0xfffffc00, v2
	v_sub_u32_e32 v1, v1, v2
	v_lshrrev_b32_e32 v2, 4, v1
	v_ashrrev_i32_e32 v4, 31, v0
	v_bitop3_b32 v1, v2, v1, 32 bitop3:0x6c
	v_lshrrev_b32_e32 v4, 26, v4
	v_ashrrev_i32_e32 v2, 31, v1
	v_add_u32_e32 v0, v0, v4
	s_waitcnt lgkmcnt(0)
	s_add_u32 s43, s4, 0xf800000
	v_lshrrev_b32_e32 v2, 26, v2
	s_waitcnt vmcnt(20)
	v_ashrrev_i32_e32 v13, 6, v0
	s_addc_u32 s44, s5, 0
	v_add_u32_e32 v2, v1, v2
	v_lshlrev_b32_e32 v0, 3, v13
	s_add_u32 s45, s4, 0x1800000
	v_ashrrev_i32_e32 v12, 6, v2
	v_and_b32_e32 v0, -16, v0
	s_addc_u32 s46, s5, 0
	v_add_u32_e32 v0, v12, v0
	v_and_b32_e32 v4, 3, v12
	s_ashr_i32 s48, s42, 31
	v_and_or_b32 v4, v0, s6, v4
	s_lshr_b32 s6, s48, 29
	s_add_i32 s6, s42, s6
	s_ashr_i32 s16, s18, 6
	s_ashr_i32 s7, s6, 3
	s_and_b32 s6, s6, -8
	s_ashr_i32 s17, s18, 8
	s_lshl_b32 s47, s16, 10
	s_sub_i32 s6, s42, s6
	s_cmp_lt_i32 s6, 0
	s_movk_i32 s49, 0x161
	s_cselect_b32 s8, s49, 0x160
	s_mul_i32 s6, s8, s6
	s_add_i32 s6, s6, s7
	s_mul_hi_i32 s7, s6, 0x2e8ba2e9
	s_lshr_b32 s8, s7, 31
	s_ashr_i32 s7, s7, 5
	s_add_i32 s7, s7, s8
	s_lshl_b32 s8, s7, 3
	s_mulk_i32 s7, 0xb0
	s_sub_i32 s7, s6, s7
	s_bfe_u32 s6, s7, 0x3001c
	s_add_i32 s9, s7, s6
	s_sext_i32_i16 s6, s9
	s_and_b32 s9, s9, 0xfff8
	s_sub_i32 s7, s7, s9
	s_sext_i32_i16 s7, s7
	v_lshrrev_b32_e32 v5, 2, v0
	v_lshlrev_b32_e32 v6, 1, v0
	v_and_b32_e32 v2, 0xc0, v2
	s_lshr_b32 s6, s6, 3
	s_add_i32 s30, s8, s7
	v_and_b32_e32 v5, 4, v5
	v_and_b32_e32 v6, 24, v6
	v_sub_u32_e32 v1, v1, v2
	s_ashr_i32 s31, s30, 31
	s_bfe_i64 s[12:13], s[6:7], 0x100000
	v_or3_b32 v4, v4, v5, v6
	v_lshlrev_b32_e32 v5, 5, v13
	v_ashrrev_i16_sdwa v1, v3, sext(v1) dst_sel:DWORD dst_unused:UNUSED_PAD src0_sel:DWORD src1_sel:BYTE_0
	s_lshl_b64 s[8:9], s[30:31], 19
	s_lshl_b64 s[12:13], s[12:13], 19
	v_and_b32_e32 v5, 32, v5
	v_bfe_i32 v14, v1, 0, 16
	s_add_u32 s38, s45, s12
	v_add_lshl_u32 v1, v5, v14, 1
	s_addc_u32 s39, s46, s13
	s_add_i32 s50, s47, 0
	v_lshl_add_u32 v132, v4, 11, v1
	s_add_i32 m0, s50, 0x10000
	v_lshl_add_u32 v134, v0, 11, v1
	s_lshl_b32 s90, s30, 8
	s_lshl_b32 s91, s17, 6
	s_add_i32 s90, s90, s91
	s_add_u32 s92, s4, 0x100000
	s_addc_u32 s93, s5, 0
	v_and_or_b32 v232, v8, 15, s90
	v_mov_b32_e32 v233, 0
	v_lshl_add_u64 v[232:233], v[232:233], 2, s[92:93]
	global_load_dword v224, v[232:233], off
	global_load_dword v225, v[232:233], off offset:64
	global_load_dword v226, v[232:233], off offset:128
	global_load_dword v227, v[232:233], off offset:192
	global_load_dword v228, v[232:233], off offset:512
	global_load_dword v229, v[232:233], off offset:576
	global_load_dword v230, v[232:233], off offset:640
	global_load_dword v231, v[232:233], off offset:704
	global_load_lds_dwordx4 v132, s[38:39]
	s_add_i32 m0, s50, 0x12000
	s_add_u32 s12, s38, 0x40000
	global_load_lds_dwordx4 v128, s[38:39]
	s_addc_u32 s13, s39, 0
	s_add_i32 m0, s50, 0x14000
	v_mov_b32_e32 v133, 0
	global_load_lds_dwordx4 v132, s[12:13]
	s_add_i32 m0, s50, 0x16000
	s_add_u32 s36, s43, s8
	s_addc_u32 s37, s44, s9
	s_add_i32 s51, s50, 0x2000
	global_load_lds_dwordx4 v128, s[12:13]
	s_mov_b32 m0, s50
	s_add_u32 s8, s36, 0x40000
	global_load_lds_dwordx4 v134, s[36:37]
	s_mov_b32 m0, s51
	s_addc_u32 s9, s37, 0
	s_add_i32 s54, s50, 0x4000
	global_load_lds_dwordx4 v130, s[36:37]
	s_mov_b32 m0, s54
	s_add_i32 s55, s50, 0x6000
	global_load_lds_dwordx4 v134, s[8:9]
	s_mov_b32 m0, s55
	v_mov_b32_e32 v129, v133
	global_load_lds_dwordx4 v130, s[8:9]
	v_mov_b32_e32 v135, v133
	v_mov_b32_e32 v131, v133
	s_cmp_eq_u32 s17, 1
	s_mov_b32 s7, 0
	v_lshl_add_u64 v[6:7], s[38:39], 0, v[132:133]
	v_lshl_add_u64 v[4:5], s[38:39], 0, v[128:129]
	v_lshl_add_u64 v[0:1], s[36:37], 0, v[134:135]
	s_cselect_b64 s[8:9], -1, 0
	s_cmp_lg_u32 s17, 1
	v_lshl_add_u64 v[2:3], s[36:37], 0, v[130:131]
	s_cbranch_scc1 .LBB0_778
	s_barrier

.LBB0_787:
	s_lshl_b32 s23, s30, 8
	s_add_i32 s23, s23, s56
	v_mbcnt_lo_u32_b32 v146, -1, 0
	v_mbcnt_hi_u32_b32 v146, -1, v146
	s_lshl_b32 s30, s21, 7
	v_and_or_b32 v148, v146, 15, s23
	v_ashrrev_i32_e32 v149, 31, v148
	v_lshl_add_u64 v[144:145], v[148:149], 2, s[12:13]
	v_mov_b32_e32 v167, v224
	v_or_b32_e32 v158, 16, v148
	v_ashrrev_i32_e32 v159, 31, v158
	v_lshl_add_u64 v[144:145], v[158:159], 2, s[12:13]
	v_mov_b32_e32 v159, v225
	v_ashrrev_i32_e32 v146, 1, v146
	v_mov_b64_e32 v[144:145], s[14:15]
	s_ashr_i32 s31, s30, 31
	v_and_b32_e32 v168, -8, v146
	v_or_b32_e32 v160, 32, v148
	s_lshl_b64 s[30:31], s[30:31], 1
	v_or_b32_e32 v156, 48, v148
	v_add_u32_e32 v154, 0x80, v148
	v_add_u32_e32 v152, 0x90, v148
	v_add_u32_e32 v150, 0xa0, v148
	v_add_u32_e32 v146, 0xb0, v148
	v_ashrrev_i32_e32 v169, 31, v168
	v_mad_i64_i32 v[148:149], s[36:37], v148, s61, v[144:145]
	v_ashrrev_i32_e32 v161, 31, v160
	v_ashrrev_i32_e32 v157, 31, v156
	v_ashrrev_i32_e32 v155, 31, v154
	v_ashrrev_i32_e32 v153, 31, v152
	v_ashrrev_i32_e32 v151, 31, v150
	v_ashrrev_i32_e32 v147, 31, v146
	v_lshl_add_u64 v[170:171], v[148:149], 0, s[30:31]
	v_lshlrev_b64 v[148:149], 1, v[168:169]
	v_lshl_add_u64 v[168:169], v[160:161], 2, s[12:13]
	v_lshl_add_u64 v[172:173], v[156:157], 2, s[12:13]
	v_lshl_add_u64 v[174:175], v[154:155], 2, s[12:13]
	v_lshl_add_u64 v[176:177], v[152:153], 2, s[12:13]
	v_lshl_add_u64 v[178:179], v[150:151], 2, s[12:13]
	v_lshl_add_u64 v[180:181], v[146:147], 2, s[12:13]
	v_mov_b32_e32 v153, v226
	v_mov_b32_e32 v155, v227
	v_mov_b32_e32 v157, v228
	v_mov_b32_e32 v161, v229
	v_mov_b32_e32 v151, v230
	v_mov_b32_e32 v147, v231
	s_mov_b32 s21, s7
	v_lshl_add_u64 v[170:171], v[170:171], 0, s[20:21]
	v_lshl_add_u64 v[170:171], v[170:171], 0, v[148:149]
	s_lshl_b32 s90, s22, 8
	s_add_i32 s90, s90, s56
	s_cmp_lg_u64 s[4:5], 0
	s_cselect_b32 s90, s90, s23
	v_mbcnt_lo_u32_b32 v232, -1, 0
	v_mbcnt_hi_u32_b32 v232, -1, v232
	v_and_or_b32 v232, v232, 15, s90
	v_mov_b32_e32 v233, 0
	v_lshl_add_u64 v[232:233], v[232:233], 2, s[12:13]
	global_load_dword v224, v[232:233], off
	global_load_dword v225, v[232:233], off offset:64
	global_load_dword v226, v[232:233], off offset:128
	global_load_dword v227, v[232:233], off offset:192
	global_load_dword v228, v[232:233], off offset:512
	global_load_dword v229, v[232:233], off offset:576
	global_load_dword v230, v[232:233], off offset:640
	global_load_dword v231, v[232:233], off offset:704
	s_andn2_b64 vcc, exec, s[4:5]
	s_mov_b64 s[4:5], -1
	s_cmp_eq_u64 s[18:19], 0
	s_cbranch_scc1 .Lalign_1
	s_barrier
.Lalign_1:
	v_fmamk_f32 v167, v167, 0x3a800000, v166
	v_rsq_f32_e32 v168, v167
	v_fmamk_f32 v159, v159, 0x3a800000, v166
	v_pk_mul_f32 v[124:125], v[124:125], v[168:169] op_sel_hi:[1,0]
	v_pk_mul_f32 v[126:127], v[126:127], v[168:169] op_sel_hi:[1,0]
	v_pk_mul_f32 v[120:121], v[120:121], v[168:169] op_sel_hi:[1,0]
	v_pk_mul_f32 v[122:123], v[122:123], v[168:169] op_sel_hi:[1,0]
	v_rsq_f32_e32 v172, v159
	v_pk_mul_f32 v[116:117], v[116:117], v[168:169] op_sel_hi:[1,0]
	v_pk_mul_f32 v[118:119], v[118:119], v[168:169] op_sel_hi:[1,0]
	v_pk_mul_f32 v[112:113], v[112:113], v[168:169] op_sel_hi:[1,0]
	v_pk_mul_f32 v[114:115], v[114:115], v[168:169] op_sel_hi:[1,0]
	v_mul_f32_e32 v159, 0xbfb8aa3b, v124
	v_mul_f32_e32 v167, 0xbfb8aa3b, v125
	v_mul_f32_e32 v168, 0xbfb8aa3b, v126
	v_mul_f32_e32 v169, 0xbfb8aa3b, v127
	v_mul_f32_e32 v173, 0xbfb8aa3b, v120
	v_mul_f32_e32 v174, 0xbfb8aa3b, v121
	v_mul_f32_e32 v175, 0xbfb8aa3b, v122
	v_mul_f32_e32 v176, 0xbfb8aa3b, v123
	v_exp_f32_e32 v159, v159
	v_exp_f32_e32 v167, v167
	v_exp_f32_e32 v168, v168
	v_exp_f32_e32 v169, v169
	v_exp_f32_e32 v173, v173
	v_exp_f32_e32 v174, v174
	v_exp_f32_e32 v175, v175
	v_exp_f32_e32 v176, v176
	v_add_f32_e32 v159, 1.0, v159
	v_add_f32_e32 v167, 1.0, v167
	v_add_f32_e32 v177, 1.0, v168
	v_add_f32_e32 v178, 1.0, v169
	v_add_f32_e32 v173, 1.0, v173
	v_add_f32_e32 v179, 1.0, v174
	v_add_f32_e32 v180, 1.0, v175
	v_add_f32_e32 v181, 1.0, v176
	v_rcp_f32_e32 v168, v159
	v_rcp_f32_e32 v169, v167
	v_rcp_f32_e32 v174, v177
	v_rcp_f32_e32 v175, v178
	v_rcp_f32_e32 v176, v173
	v_rcp_f32_e32 v177, v179
	v_rcp_f32_e32 v178, v180
	v_rcp_f32_e32 v179, v181
	v_pk_mul_f32 v[124:125], v[124:125], v[168:169]
	v_pk_mul_f32 v[126:127], v[126:127], v[174:175]
	v_pk_mul_f32 v[120:121], v[120:121], v[176:177]
	v_pk_mul_f32 v[122:123], v[122:123], v[178:179]
	v_pk_mul_f32 v[116:117], v[116:117], v[124:125]
	v_pk_mul_f32 v[118:119], v[118:119], v[126:127]
	v_pk_mul_f32 v[120:121], v[112:113], v[120:121]
	v_pk_mul_f32 v[122:123], v[114:115], v[122:123]
	v_cvt_pk_bf16_f32 v112, v116, v117
	v_cvt_pk_bf16_f32 v113, v118, v119
	v_cvt_pk_bf16_f32 v114, v120, v121
	v_cvt_pk_bf16_f32 v115, v122, v123
	v_pk_mul_f32 v[108:109], v[108:109], v[172:173] op_sel_hi:[1,0]
	global_store_dwordx4 v[170:171], v[112:115], off
	v_mul_f32_e32 v116, 0xbfb8aa3b, v108
	v_pk_mul_f32 v[110:111], v[110:111], v[172:173] op_sel_hi:[1,0]
	v_mul_f32_e32 v112, 0xbfb8aa3b, v109
	v_exp_f32_e32 v116, v116
	v_exp_f32_e32 v113, v112
	v_mul_f32_e32 v114, 0xbfb8aa3b, v110
	v_mul_f32_e32 v115, 0xbfb8aa3b, v111
	v_exp_f32_e32 v114, v114
	v_exp_f32_e32 v115, v115
	v_add_f32_e32 v112, 1.0, v116
	v_add_f32_e32 v113, 1.0, v113
	v_rcp_f32_e32 v112, v112
	v_rcp_f32_e32 v113, v113
	v_add_f32_e32 v114, 1.0, v114
	v_add_f32_e32 v115, 1.0, v115
	v_rcp_f32_e32 v114, v114
	v_rcp_f32_e32 v115, v115
	v_pk_mul_f32 v[100:101], v[100:101], v[172:173] op_sel_hi:[1,0]
	v_pk_mul_f32 v[108:109], v[108:109], v[112:113]
	v_pk_mul_f32 v[104:105], v[104:105], v[172:173] op_sel_hi:[1,0]
	v_pk_mul_f32 v[100:101], v[100:101], v[108:109]
	v_pk_mul_f32 v[108:109], v[110:111], v[114:115]
	v_mul_f32_e32 v110, 0xbfb8aa3b, v104
	v_exp_f32_e32 v110, v110
	v_pk_mul_f32 v[102:103], v[102:103], v[172:173] op_sel_hi:[1,0]
	v_pk_mul_f32 v[106:107], v[106:107], v[172:173] op_sel_hi:[1,0]
	v_pk_mul_f32 v[102:103], v[102:103], v[108:109]
	v_mul_f32_e32 v108, 0xbfb8aa3b, v105
	v_exp_f32_e32 v109, v108
	v_add_f32_e32 v108, 1.0, v110
	v_mul_f32_e32 v110, 0xbfb8aa3b, v106
	v_mul_f32_e32 v111, 0xbfb8aa3b, v107
	v_exp_f32_e32 v110, v110
	v_exp_f32_e32 v111, v111
	v_add_f32_e32 v109, 1.0, v109
	v_rcp_f32_e32 v108, v108
	v_rcp_f32_e32 v109, v109
	v_add_f32_e32 v110, 1.0, v110
	v_add_f32_e32 v111, 1.0, v111
	v_rcp_f32_e32 v110, v110
	v_rcp_f32_e32 v111, v111
	v_pk_mul_f32 v[96:97], v[96:97], v[172:173] op_sel_hi:[1,0]
	v_pk_mul_f32 v[104:105], v[104:105], v[108:109]
	s_nop 0
	v_pk_mul_f32 v[104:105], v[96:97], v[104:105]
	v_pk_mul_f32 v[96:97], v[98:99], v[172:173] op_sel_hi:[1,0]
	v_pk_mul_f32 v[98:99], v[106:107], v[110:111]
	s_nop 0
	v_pk_mul_f32 v[106:107], v[96:97], v[98:99]
	v_mad_i64_i32 v[96:97], s[36:37], v158, s61, v[144:145]
	v_lshl_add_u64 v[96:97], v[96:97], 0, s[30:31]
	v_lshl_add_u64 v[96:97], v[96:97], 0, s[20:21]
	v_lshl_add_u64 v[108:109], v[96:97], 0, v[148:149]
	v_fmamk_f32 v97, v153, 0x3a800000, v166
	v_cvt_pk_bf16_f32 v96, v100, v101
	v_rsq_f32_e32 v100, v97
	v_cvt_pk_bf16_f32 v97, v102, v103
	v_cvt_pk_bf16_f32 v98, v104, v105
	v_cvt_pk_bf16_f32 v99, v106, v107
	v_pk_mul_f32 v[92:93], v[92:93], v[100:101] op_sel_hi:[1,0]
	global_store_dwordx4 v[108:109], v[96:99], off
	v_mul_f32_e32 v101, 0xbfb8aa3b, v92
	v_exp_f32_e32 v101, v101
	v_mul_f32_e32 v96, 0xbfb8aa3b, v93
	v_exp_f32_e32 v97, v96
	v_pk_mul_f32 v[94:95], v[94:95], v[100:101] op_sel_hi:[1,0]
	s_nop 0
	v_mul_f32_e32 v98, 0xbfb8aa3b, v94
	v_mul_f32_e32 v99, 0xbfb8aa3b, v95
	v_exp_f32_e32 v98, v98
	v_exp_f32_e32 v99, v99
	v_add_f32_e32 v96, 1.0, v101
	v_add_f32_e32 v97, 1.0, v97
	v_rcp_f32_e32 v96, v96
	v_rcp_f32_e32 v97, v97
	v_add_f32_e32 v98, 1.0, v98
	v_add_f32_e32 v99, 1.0, v99
	v_rcp_f32_e32 v98, v98
	v_rcp_f32_e32 v99, v99
	v_pk_mul_f32 v[84:85], v[84:85], v[100:101] op_sel_hi:[1,0]
	v_pk_mul_f32 v[92:93], v[92:93], v[96:97]
	v_pk_mul_f32 v[88:89], v[88:89], v[100:101] op_sel_hi:[1,0]
	v_pk_mul_f32 v[84:85], v[84:85], v[92:93]
	v_pk_mul_f32 v[92:93], v[94:95], v[98:99]
	v_mul_f32_e32 v94, 0xbfb8aa3b, v88
	v_exp_f32_e32 v94, v94
	v_pk_mul_f32 v[86:87], v[86:87], v[100:101] op_sel_hi:[1,0]
	v_pk_mul_f32 v[90:91], v[90:91], v[100:101] op_sel_hi:[1,0]
	v_pk_mul_f32 v[86:87], v[86:87], v[92:93]
	v_mul_f32_e32 v92, 0xbfb8aa3b, v89
	v_exp_f32_e32 v93, v92
	v_add_f32_e32 v92, 1.0, v94
	v_mul_f32_e32 v94, 0xbfb8aa3b, v90
	v_mul_f32_e32 v95, 0xbfb8aa3b, v91
	v_exp_f32_e32 v94, v94
	v_exp_f32_e32 v95, v95
	v_add_f32_e32 v93, 1.0, v93
	v_rcp_f32_e32 v92, v92
	v_rcp_f32_e32 v93, v93
	v_add_f32_e32 v94, 1.0, v94
	v_add_f32_e32 v95, 1.0, v95
	v_rcp_f32_e32 v94, v94
	v_rcp_f32_e32 v95, v95
	v_pk_mul_f32 v[80:81], v[80:81], v[100:101] op_sel_hi:[1,0]
	v_pk_mul_f32 v[88:89], v[88:89], v[92:93]
	s_nop 0
	v_pk_mul_f32 v[88:89], v[80:81], v[88:89]
	v_pk_mul_f32 v[80:81], v[82:83], v[100:101] op_sel_hi:[1,0]
	v_pk_mul_f32 v[82:83], v[90:91], v[94:95]
	s_nop 0
	v_pk_mul_f32 v[90:91], v[80:81], v[82:83]
	v_mad_i64_i32 v[80:81], s[36:37], v160, s61, v[144:145]
	v_lshl_add_u64 v[80:81], v[80:81], 0, s[30:31]
	v_lshl_add_u64 v[80:81], v[80:81], 0, s[20:21]
	v_lshl_add_u64 v[92:93], v[80:81], 0, v[148:149]
	v_fmamk_f32 v81, v155, 0x3a800000, v166
	v_cvt_pk_bf16_f32 v80, v84, v85
	v_rsq_f32_e32 v84, v81
	v_cvt_pk_bf16_f32 v81, v86, v87
	v_cvt_pk_bf16_f32 v82, v88, v89
	v_cvt_pk_bf16_f32 v83, v90, v91
	v_pk_mul_f32 v[76:77], v[76:77], v[84:85] op_sel_hi:[1,0]
	global_store_dwordx4 v[92:93], v[80:83], off
	v_mul_f32_e32 v85, 0xbfb8aa3b, v76
	v_exp_f32_e32 v85, v85
	v_mul_f32_e32 v80, 0xbfb8aa3b, v77
	v_exp_f32_e32 v81, v80
	v_pk_mul_f32 v[78:79], v[78:79], v[84:85] op_sel_hi:[1,0]
	s_nop 0
	v_mul_f32_e32 v82, 0xbfb8aa3b, v78
	v_mul_f32_e32 v83, 0xbfb8aa3b, v79
	v_exp_f32_e32 v82, v82
	v_exp_f32_e32 v83, v83
	v_add_f32_e32 v80, 1.0, v85
	v_add_f32_e32 v81, 1.0, v81
	v_rcp_f32_e32 v80, v80
	v_rcp_f32_e32 v81, v81
	v_add_f32_e32 v82, 1.0, v82
	v_add_f32_e32 v83, 1.0, v83
	v_rcp_f32_e32 v82, v82
	v_rcp_f32_e32 v83, v83
	v_pk_mul_f32 v[68:69], v[68:69], v[84:85] op_sel_hi:[1,0]
	v_pk_mul_f32 v[76:77], v[76:77], v[80:81]
	v_pk_mul_f32 v[72:73], v[72:73], v[84:85] op_sel_hi:[1,0]
	v_pk_mul_f32 v[68:69], v[68:69], v[76:77]
	v_pk_mul_f32 v[76:77], v[78:79], v[82:83]
	v_mul_f32_e32 v78, 0xbfb8aa3b, v72
	v_exp_f32_e32 v78, v78
	v_pk_mul_f32 v[70:71], v[70:71], v[84:85] op_sel_hi:[1,0]
	v_pk_mul_f32 v[74:75], v[74:75], v[84:85] op_sel_hi:[1,0]
	v_pk_mul_f32 v[70:71], v[70:71], v[76:77]
	v_mul_f32_e32 v76, 0xbfb8aa3b, v73
	v_exp_f32_e32 v77, v76
	v_add_f32_e32 v76, 1.0, v78
	v_mul_f32_e32 v78, 0xbfb8aa3b, v74
	v_mul_f32_e32 v79, 0xbfb8aa3b, v75
	v_exp_f32_e32 v78, v78
	v_exp_f32_e32 v79, v79
	v_add_f32_e32 v77, 1.0, v77
	v_rcp_f32_e32 v76, v76
	v_rcp_f32_e32 v77, v77
	v_add_f32_e32 v78, 1.0, v78
	v_add_f32_e32 v79, 1.0, v79
	v_rcp_f32_e32 v78, v78
	v_rcp_f32_e32 v79, v79
	v_pk_mul_f32 v[64:65], v[64:65], v[84:85] op_sel_hi:[1,0]
	v_pk_mul_f32 v[72:73], v[72:73], v[76:77]
	s_nop 0
	v_pk_mul_f32 v[72:73], v[64:65], v[72:73]
	v_pk_mul_f32 v[64:65], v[66:67], v[84:85] op_sel_hi:[1,0]
	v_pk_mul_f32 v[66:67], v[74:75], v[78:79]
	s_nop 0
	v_pk_mul_f32 v[74:75], v[64:65], v[66:67]
	v_mad_i64_i32 v[64:65], s[36:37], v156, s61, v[144:145]
	v_lshl_add_u64 v[64:65], v[64:65], 0, s[30:31]
	v_lshl_add_u64 v[64:65], v[64:65], 0, s[20:21]
	v_fmamk_f32 v66, v157, 0x3a800000, v166
	v_lshl_add_u64 v[76:77], v[64:65], 0, v[148:149]
	v_cvt_pk_bf16_f32 v64, v68, v69
	v_rsq_f32_e32 v68, v66
	v_cvt_pk_bf16_f32 v65, v70, v71
	v_cvt_pk_bf16_f32 v66, v72, v73
	v_cvt_pk_bf16_f32 v67, v74, v75
	v_pk_mul_f32 v[60:61], v[60:61], v[68:69] op_sel_hi:[1,0]
	global_store_dwordx4 v[76:77], v[64:67], off
	v_pk_mul_f32 v[62:63], v[62:63], v[68:69] op_sel_hi:[1,0]
	v_pk_mul_f32 v[52:53], v[52:53], v[68:69] op_sel_hi:[1,0]
	v_mul_f32_e32 v64, 0xbfb8aa3b, v60
	v_mul_f32_e32 v65, 0xbfb8aa3b, v61
	v_exp_f32_e32 v64, v64
	v_exp_f32_e32 v65, v65
	v_mul_f32_e32 v66, 0xbfb8aa3b, v62
	v_mul_f32_e32 v67, 0xbfb8aa3b, v63
	v_exp_f32_e32 v66, v66
	v_exp_f32_e32 v67, v67
	v_add_f32_e32 v64, 1.0, v64
	v_add_f32_e32 v65, 1.0, v65
	v_rcp_f32_e32 v64, v64
	v_rcp_f32_e32 v65, v65
	v_add_f32_e32 v66, 1.0, v66
	v_add_f32_e32 v67, 1.0, v67
	v_rcp_f32_e32 v66, v66
	v_rcp_f32_e32 v67, v67
	v_pk_mul_f32 v[60:61], v[60:61], v[64:65]
	v_pk_mul_f32 v[56:57], v[56:57], v[68:69] op_sel_hi:[1,0]
	v_pk_mul_f32 v[52:53], v[52:53], v[60:61]
	v_pk_mul_f32 v[60:61], v[62:63], v[66:67]
	v_mul_f32_e32 v62, 0xbfb8aa3b, v56
	v_exp_f32_e32 v62, v62
	v_pk_mul_f32 v[54:55], v[54:55], v[68:69] op_sel_hi:[1,0]
	v_pk_mul_f32 v[58:59], v[58:59], v[68:69] op_sel_hi:[1,0]
	v_pk_mul_f32 v[54:55], v[54:55], v[60:61]
	v_mul_f32_e32 v60, 0xbfb8aa3b, v57
	v_exp_f32_e32 v61, v60
	v_add_f32_e32 v60, 1.0, v62
	v_mul_f32_e32 v62, 0xbfb8aa3b, v58
	v_mul_f32_e32 v63, 0xbfb8aa3b, v59
	v_exp_f32_e32 v62, v62
	v_exp_f32_e32 v63, v63
	v_add_f32_e32 v61, 1.0, v61
	v_rcp_f32_e32 v60, v60
	v_rcp_f32_e32 v61, v61
	v_add_f32_e32 v62, 1.0, v62
	v_add_f32_e32 v63, 1.0, v63
	v_rcp_f32_e32 v62, v62
	v_rcp_f32_e32 v63, v63
	v_pk_mul_f32 v[48:49], v[48:49], v[68:69] op_sel_hi:[1,0]
	v_pk_mul_f32 v[56:57], v[56:57], v[60:61]
	s_nop 0
	v_pk_mul_f32 v[56:57], v[48:49], v[56:57]
	v_pk_mul_f32 v[48:49], v[50:51], v[68:69] op_sel_hi:[1,0]
	v_pk_mul_f32 v[50:51], v[58:59], v[62:63]
	s_nop 0
	v_pk_mul_f32 v[58:59], v[48:49], v[50:51]
	v_mad_i64_i32 v[48:49], s[36:37], v154, s61, v[144:145]
	v_lshl_add_u64 v[48:49], v[48:49], 0, s[30:31]
	v_lshl_add_u64 v[48:49], v[48:49], 0, s[20:21]
	v_lshl_add_u64 v[60:61], v[48:49], 0, v[148:149]
	v_fmamk_f32 v49, v161, 0x3a800000, v166
	v_cvt_pk_bf16_f32 v48, v52, v53
	v_rsq_f32_e32 v52, v49
	v_cvt_pk_bf16_f32 v49, v54, v55
	v_cvt_pk_bf16_f32 v50, v56, v57
	v_cvt_pk_bf16_f32 v51, v58, v59
	v_pk_mul_f32 v[44:45], v[44:45], v[52:53] op_sel_hi:[1,0]
	global_store_dwordx4 v[60:61], v[48:51], off
	v_mul_f32_e32 v53, 0xbfb8aa3b, v44
	v_exp_f32_e32 v53, v53
	v_mul_f32_e32 v48, 0xbfb8aa3b, v45
	v_exp_f32_e32 v49, v48
	v_pk_mul_f32 v[46:47], v[46:47], v[52:53] op_sel_hi:[1,0]
	s_nop 0
	v_mul_f32_e32 v50, 0xbfb8aa3b, v46
	v_mul_f32_e32 v51, 0xbfb8aa3b, v47
	v_exp_f32_e32 v50, v50
	v_exp_f32_e32 v51, v51
	v_add_f32_e32 v48, 1.0, v53
	v_add_f32_e32 v49, 1.0, v49
	v_rcp_f32_e32 v48, v48
	v_rcp_f32_e32 v49, v49
	v_add_f32_e32 v50, 1.0, v50
	v_add_f32_e32 v51, 1.0, v51
	v_rcp_f32_e32 v50, v50
	v_rcp_f32_e32 v51, v51
	v_pk_mul_f32 v[36:37], v[36:37], v[52:53] op_sel_hi:[1,0]
	v_pk_mul_f32 v[44:45], v[44:45], v[48:49]
	v_pk_mul_f32 v[40:41], v[40:41], v[52:53] op_sel_hi:[1,0]
	v_pk_mul_f32 v[36:37], v[36:37], v[44:45]
	v_pk_mul_f32 v[44:45], v[46:47], v[50:51]
	v_mul_f32_e32 v46, 0xbfb8aa3b, v40
	v_exp_f32_e32 v46, v46
	v_pk_mul_f32 v[38:39], v[38:39], v[52:53] op_sel_hi:[1,0]
	v_pk_mul_f32 v[42:43], v[42:43], v[52:53] op_sel_hi:[1,0]
	v_pk_mul_f32 v[38:39], v[38:39], v[44:45]
	v_mul_f32_e32 v44, 0xbfb8aa3b, v41
	v_exp_f32_e32 v45, v44
	v_add_f32_e32 v44, 1.0, v46
	v_mul_f32_e32 v46, 0xbfb8aa3b, v42
	v_mul_f32_e32 v47, 0xbfb8aa3b, v43
	v_exp_f32_e32 v46, v46
	v_exp_f32_e32 v47, v47
	v_add_f32_e32 v45, 1.0, v45
	v_rcp_f32_e32 v44, v44
	v_rcp_f32_e32 v45, v45
	v_add_f32_e32 v46, 1.0, v46
	v_add_f32_e32 v47, 1.0, v47
	v_rcp_f32_e32 v46, v46
	v_rcp_f32_e32 v47, v47
	v_pk_mul_f32 v[32:33], v[32:33], v[52:53] op_sel_hi:[1,0]
	v_pk_mul_f32 v[40:41], v[40:41], v[44:45]
	s_nop 0
	v_pk_mul_f32 v[40:41], v[32:33], v[40:41]
	v_pk_mul_f32 v[32:33], v[34:35], v[52:53] op_sel_hi:[1,0]
	v_pk_mul_f32 v[34:35], v[42:43], v[46:47]
	s_nop 0
	v_pk_mul_f32 v[42:43], v[32:33], v[34:35]
	v_mad_i64_i32 v[32:33], s[36:37], v152, s61, v[144:145]
	v_lshl_add_u64 v[32:33], v[32:33], 0, s[30:31]
	v_lshl_add_u64 v[32:33], v[32:33], 0, s[20:21]
	v_lshl_add_u64 v[44:45], v[32:33], 0, v[148:149]
	v_fmamk_f32 v33, v151, 0x3a800000, v166
	v_cvt_pk_bf16_f32 v32, v36, v37
	v_rsq_f32_e32 v36, v33
	v_cvt_pk_bf16_f32 v33, v38, v39
	v_cvt_pk_bf16_f32 v34, v40, v41
	v_cvt_pk_bf16_f32 v35, v42, v43
	v_pk_mul_f32 v[28:29], v[28:29], v[36:37] op_sel_hi:[1,0]
	global_store_dwordx4 v[44:45], v[32:35], off
	v_mul_f32_e32 v37, 0xbfb8aa3b, v28
	v_exp_f32_e32 v37, v37
	v_mul_f32_e32 v32, 0xbfb8aa3b, v29
	v_exp_f32_e32 v33, v32
	v_pk_mul_f32 v[30:31], v[30:31], v[36:37] op_sel_hi:[1,0]
	s_nop 0
	v_mul_f32_e32 v34, 0xbfb8aa3b, v30
	v_mul_f32_e32 v35, 0xbfb8aa3b, v31
	v_exp_f32_e32 v34, v34
	v_exp_f32_e32 v35, v35
	v_add_f32_e32 v32, 1.0, v37
	v_add_f32_e32 v33, 1.0, v33
	v_rcp_f32_e32 v32, v32
	v_rcp_f32_e32 v33, v33
	v_add_f32_e32 v34, 1.0, v34
	v_add_f32_e32 v35, 1.0, v35
	v_rcp_f32_e32 v34, v34
	v_rcp_f32_e32 v35, v35
	v_pk_mul_f32 v[20:21], v[20:21], v[36:37] op_sel_hi:[1,0]
	v_pk_mul_f32 v[28:29], v[28:29], v[32:33]
	v_pk_mul_f32 v[24:25], v[24:25], v[36:37] op_sel_hi:[1,0]
	v_pk_mul_f32 v[20:21], v[20:21], v[28:29]
	v_pk_mul_f32 v[28:29], v[30:31], v[34:35]
	v_mul_f32_e32 v30, 0xbfb8aa3b, v24
	v_exp_f32_e32 v30, v30
	v_pk_mul_f32 v[22:23], v[22:23], v[36:37] op_sel_hi:[1,0]
	v_pk_mul_f32 v[26:27], v[26:27], v[36:37] op_sel_hi:[1,0]
	v_pk_mul_f32 v[22:23], v[22:23], v[28:29]
	v_mul_f32_e32 v28, 0xbfb8aa3b, v25
	v_exp_f32_e32 v29, v28
	v_add_f32_e32 v28, 1.0, v30
	v_mul_f32_e32 v30, 0xbfb8aa3b, v26
	v_mul_f32_e32 v31, 0xbfb8aa3b, v27
	v_exp_f32_e32 v30, v30
	v_exp_f32_e32 v31, v31
	v_add_f32_e32 v29, 1.0, v29
	v_rcp_f32_e32 v28, v28
	v_rcp_f32_e32 v29, v29
	v_add_f32_e32 v30, 1.0, v30
	v_add_f32_e32 v31, 1.0, v31
	v_rcp_f32_e32 v30, v30
	v_rcp_f32_e32 v31, v31
	v_pk_mul_f32 v[16:17], v[16:17], v[36:37] op_sel_hi:[1,0]
	v_pk_mul_f32 v[24:25], v[24:25], v[28:29]
	s_nop 0
	v_pk_mul_f32 v[24:25], v[16:17], v[24:25]
	v_pk_mul_f32 v[16:17], v[18:19], v[36:37] op_sel_hi:[1,0]
	v_pk_mul_f32 v[18:19], v[26:27], v[30:31]
	s_nop 0
	v_pk_mul_f32 v[26:27], v[16:17], v[18:19]
	v_mad_i64_i32 v[16:17], s[36:37], v150, s61, v[144:145]
	v_lshl_add_u64 v[16:17], v[16:17], 0, s[30:31]
	v_lshl_add_u64 v[16:17], v[16:17], 0, s[20:21]
	v_lshl_add_u64 v[28:29], v[16:17], 0, v[148:149]
	v_fmamk_f32 v17, v147, 0x3a800000, v166
	v_cvt_pk_bf16_f32 v16, v20, v21
	v_rsq_f32_e32 v20, v17
	v_cvt_pk_bf16_f32 v17, v22, v23
	v_cvt_pk_bf16_f32 v18, v24, v25
	v_cvt_pk_bf16_f32 v19, v26, v27
	v_pk_mul_f32 v[12:13], v[12:13], v[20:21] op_sel_hi:[1,0]
	global_store_dwordx4 v[28:29], v[16:19], off
	v_mul_f32_e32 v21, 0xbfb8aa3b, v12
	v_exp_f32_e32 v21, v21
	v_mul_f32_e32 v16, 0xbfb8aa3b, v13
	v_exp_f32_e32 v17, v16
	v_pk_mul_f32 v[14:15], v[14:15], v[20:21] op_sel_hi:[1,0]
	s_nop 0
	v_mul_f32_e32 v18, 0xbfb8aa3b, v14
	v_mul_f32_e32 v19, 0xbfb8aa3b, v15
	v_exp_f32_e32 v18, v18
	v_exp_f32_e32 v19, v19
	v_add_f32_e32 v16, 1.0, v21
	v_add_f32_e32 v17, 1.0, v17
	v_rcp_f32_e32 v16, v16
	v_rcp_f32_e32 v17, v17
	v_add_f32_e32 v18, 1.0, v18
	v_add_f32_e32 v19, 1.0, v19
	v_rcp_f32_e32 v18, v18
	v_rcp_f32_e32 v19, v19
	v_pk_mul_f32 v[4:5], v[4:5], v[20:21] op_sel_hi:[1,0]
	v_pk_mul_f32 v[12:13], v[12:13], v[16:17]
	v_pk_mul_f32 v[8:9], v[8:9], v[20:21] op_sel_hi:[1,0]
	v_pk_mul_f32 v[4:5], v[4:5], v[12:13]
	v_pk_mul_f32 v[12:13], v[14:15], v[18:19]
	v_mul_f32_e32 v14, 0xbfb8aa3b, v8
	v_exp_f32_e32 v14, v14
	v_pk_mul_f32 v[6:7], v[6:7], v[20:21] op_sel_hi:[1,0]
	v_pk_mul_f32 v[10:11], v[10:11], v[20:21] op_sel_hi:[1,0]
	v_pk_mul_f32 v[6:7], v[6:7], v[12:13]
	v_mul_f32_e32 v12, 0xbfb8aa3b, v9
	v_exp_f32_e32 v13, v12
	v_add_f32_e32 v12, 1.0, v14
	v_mul_f32_e32 v14, 0xbfb8aa3b, v10
	v_mul_f32_e32 v15, 0xbfb8aa3b, v11
	v_exp_f32_e32 v14, v14
	v_exp_f32_e32 v15, v15
	v_add_f32_e32 v13, 1.0, v13
	v_rcp_f32_e32 v12, v12
	v_rcp_f32_e32 v13, v13
	v_add_f32_e32 v14, 1.0, v14
	v_add_f32_e32 v15, 1.0, v15
	v_rcp_f32_e32 v14, v14
	v_rcp_f32_e32 v15, v15
	v_pk_mul_f32 v[0:1], v[0:1], v[20:21] op_sel_hi:[1,0]
	v_pk_mul_f32 v[8:9], v[8:9], v[12:13]
	s_nop 0
	v_pk_mul_f32 v[8:9], v[0:1], v[8:9]
	v_pk_mul_f32 v[0:1], v[2:3], v[20:21] op_sel_hi:[1,0]
	v_pk_mul_f32 v[2:3], v[10:11], v[14:15]
	s_nop 0
	v_pk_mul_f32 v[10:11], v[0:1], v[2:3]
	v_mad_i64_i32 v[0:1], s[36:37], v146, s61, v[144:145]
	v_lshl_add_u64 v[0:1], v[0:1], 0, s[30:31]
	v_lshl_add_u64 v[0:1], v[0:1], 0, s[20:21]
	v_lshl_add_u64 v[12:13], v[0:1], 0, v[148:149]
	v_cvt_pk_bf16_f32 v0, v4, v5
	v_cvt_pk_bf16_f32 v1, v6, v7
	v_cvt_pk_bf16_f32 v2, v8, v9
	v_cvt_pk_bf16_f32 v3, v10, v11
	global_store_dwordx4 v[12:13], v[0:3], off
	s_cbranch_vccnz .LBB0_780
	s_andn2_b64 vcc, exec, s[8:9]
	s_cbranch_vccnz .LBB0_779
	s_barrier
	s_branch .LBB0_779

.LBB0_1221:
	s_or_b64 exec, exec, s[4:5]
	s_mov_b64 s[4:5], s[0:1]
	s_mov_b32 s42, s2
	s_waitcnt lgkmcnt(0)
	s_barrier
	v_mbcnt_lo_u32_b32 v8, -1, 0
	v_mbcnt_hi_u32_b32 v8, -1, v8
	s_cmpk_gt_i32 s42, 0xaff
	v_add_u32_e32 v0, s33, v8
	s_nop 0
	v_readfirstlane_b32 s18, v0
	s_cbranch_scc1 .LBB0_1237
	v_lshlrev_b32_e32 v1, 4, v0
	v_add_u32_e32 v2, 0x2000, v1
	v_ashrrev_i32_e32 v3, 31, v2
	v_lshrrev_b32_e32 v3, 22, v3
	v_add_u32_e32 v3, v2, v3
	v_ashrrev_i32_e32 v9, 10, v3
	v_mul_i32_i24_e32 v3, 0x400, v9
	v_sub_u32_e32 v2, v2, v3
	v_lshrrev_b32_e32 v3, 4, v2
	v_bitop3_b32 v2, v3, v2, 32 bitop3:0x6c
	v_ashrrev_i32_e32 v3, 31, v2
	v_lshrrev_b32_e32 v3, 26, v3
	v_add_u32_e32 v3, v2, v3
	v_lshlrev_b32_e32 v4, 3, v9
	v_ashrrev_i32_e32 v10, 6, v3
	v_and_b32_e32 v4, -16, v4
	v_add_u32_e32 v4, v10, v4
	v_and_b32_e32 v5, 3, v10
	s_mov_b32 s6, 0x1fffe0
	v_lshrrev_b32_e32 v6, 2, v4
	v_lshlrev_b32_e32 v7, 1, v4
	v_and_b32_e32 v3, 0xc0, v3
	v_and_or_b32 v5, v4, s6, v5
	v_and_b32_e32 v6, 4, v6
	v_and_b32_e32 v7, 24, v7
	v_sub_u32_e32 v2, v2, v3
	v_mov_b32_e32 v3, 1
	v_or3_b32 v5, v5, v6, v7
	v_lshlrev_b32_e32 v6, 5, v9
	v_ashrrev_i16_sdwa v2, v3, sext(v2) dst_sel:DWORD dst_unused:UNUSED_PAD src0_sel:DWORD src1_sel:BYTE_0
	v_and_b32_e32 v6, 32, v6
	v_bfe_i32 v11, v2, 0, 16
	v_add_lshl_u32 v2, v6, v11, 1
	v_lshl_add_u32 v128, v5, 11, v2
	v_lshl_add_u32 v130, v4, 11, v2
	v_bfe_i32 v2, v0, 27, 1
	v_lshrrev_b32_e32 v2, 22, v2
	v_add_u32_e32 v2, v1, v2
	s_load_dwordx2 s[4:5], s[4:5], 0xa0
	v_and_b32_e32 v2, 0xfffffc00, v2
	v_sub_u32_e32 v1, v1, v2
	v_lshrrev_b32_e32 v2, 4, v1
	v_ashrrev_i32_e32 v4, 31, v0
	v_bitop3_b32 v1, v2, v1, 32 bitop3:0x6c
	v_lshrrev_b32_e32 v4, 26, v4
	v_ashrrev_i32_e32 v2, 31, v1
	v_add_u32_e32 v0, v0, v4
	s_waitcnt lgkmcnt(0)
	s_add_u32 s43, s4, 0x14800000
	v_lshrrev_b32_e32 v2, 26, v2
	v_ashrrev_i32_e32 v13, 6, v0
	s_addc_u32 s44, s5, 0
	v_add_u32_e32 v2, v1, v2
	v_lshlrev_b32_e32 v0, 3, v13
	s_add_u32 s45, s4, 0x3100000
	v_ashrrev_i32_e32 v12, 6, v2
	v_and_b32_e32 v0, -16, v0
	s_addc_u32 s46, s5, 0
	v_add_u32_e32 v0, v12, v0
	v_and_b32_e32 v4, 3, v12
	s_ashr_i32 s48, s42, 31
	v_and_or_b32 v4, v0, s6, v4
	s_lshr_b32 s6, s48, 29
	s_add_i32 s6, s42, s6
	s_ashr_i32 s16, s18, 6
	s_ashr_i32 s7, s6, 3
	s_and_b32 s6, s6, -8
	s_ashr_i32 s17, s18, 8
	s_lshl_b32 s47, s16, 10
	s_sub_i32 s6, s42, s6
	s_cmp_lt_i32 s6, 0
	s_movk_i32 s49, 0x161
	s_cselect_b32 s8, s49, 0x160
	s_mul_i32 s6, s8, s6
	s_add_i32 s6, s6, s7
	s_mul_hi_i32 s7, s6, 0x2e8ba2e9
	s_lshr_b32 s8, s7, 31
	s_ashr_i32 s7, s7, 5
	s_add_i32 s7, s7, s8
	s_lshl_b32 s8, s7, 3
	s_mulk_i32 s7, 0xb0
	s_sub_i32 s7, s6, s7
	s_bfe_u32 s6, s7, 0x3001c
	s_add_i32 s9, s7, s6
	s_sext_i32_i16 s6, s9
	s_and_b32 s9, s9, 0xfff8
	s_sub_i32 s7, s7, s9
	s_sext_i32_i16 s7, s7
	v_lshrrev_b32_e32 v5, 2, v0
	v_lshlrev_b32_e32 v6, 1, v0
	v_and_b32_e32 v2, 0xc0, v2
	s_lshr_b32 s6, s6, 3
	s_add_i32 s30, s8, s7
	v_and_b32_e32 v5, 4, v5
	v_and_b32_e32 v6, 24, v6
	v_sub_u32_e32 v1, v1, v2
	s_ashr_i32 s31, s30, 31
	s_bfe_i64 s[12:13], s[6:7], 0x100000
	v_or3_b32 v4, v4, v5, v6
	v_lshlrev_b32_e32 v5, 5, v13
	v_ashrrev_i16_sdwa v1, v3, sext(v1) dst_sel:DWORD dst_unused:UNUSED_PAD src0_sel:DWORD src1_sel:BYTE_0
	s_lshl_b64 s[8:9], s[30:31], 19
	s_lshl_b64 s[12:13], s[12:13], 19
	v_and_b32_e32 v5, 32, v5
	v_bfe_i32 v14, v1, 0, 16
	s_add_u32 s38, s45, s12
	v_add_lshl_u32 v1, v5, v14, 1
	s_addc_u32 s39, s46, s13
	s_add_i32 s50, s47, 0
	v_lshl_add_u32 v132, v4, 11, v1
	s_add_i32 m0, s50, 0x10000
	v_lshl_add_u32 v134, v0, 11, v1
	s_lshl_b32 s90, s30, 8
	s_lshl_b32 s91, s17, 6
	s_add_i32 s90, s90, s91
	s_add_u32 s92, s4, 0x140000
	s_addc_u32 s93, s5, 0
	v_and_or_b32 v232, v8, 15, s90
	v_mov_b32_e32 v233, 0
	v_lshl_add_u64 v[232:233], v[232:233], 2, s[92:93]
	global_load_dword v224, v[232:233], off
	global_load_dword v225, v[232:233], off offset:64
	global_load_dword v226, v[232:233], off offset:128
	global_load_dword v227, v[232:233], off offset:192
	global_load_dword v228, v[232:233], off offset:512
	global_load_dword v229, v[232:233], off offset:576
	global_load_dword v230, v[232:233], off offset:640
	global_load_dword v231, v[232:233], off offset:704
	global_load_lds_dwordx4 v132, s[38:39]
	s_add_i32 m0, s50, 0x12000
	s_add_u32 s12, s38, 0x40000
	global_load_lds_dwordx4 v128, s[38:39]
	s_addc_u32 s13, s39, 0
	s_add_i32 m0, s50, 0x14000
	v_mov_b32_e32 v133, 0
	global_load_lds_dwordx4 v132, s[12:13]
	s_add_i32 m0, s50, 0x16000
	s_add_u32 s36, s43, s8
	s_addc_u32 s37, s44, s9
	s_add_i32 s51, s50, 0x2000
	global_load_lds_dwordx4 v128, s[12:13]
	s_mov_b32 m0, s50
	s_add_u32 s8, s36, 0x40000
	global_load_lds_dwordx4 v134, s[36:37]
	s_mov_b32 m0, s51
	s_addc_u32 s9, s37, 0
	s_add_i32 s54, s50, 0x4000
	global_load_lds_dwordx4 v130, s[36:37]
	s_mov_b32 m0, s54
	s_add_i32 s55, s50, 0x6000
	global_load_lds_dwordx4 v134, s[8:9]
	s_mov_b32 m0, s55
	v_mov_b32_e32 v129, v133
	global_load_lds_dwordx4 v130, s[8:9]
	v_mov_b32_e32 v135, v133
	v_mov_b32_e32 v131, v133
	s_cmp_eq_u32 s17, 1
	s_mov_b32 s7, 0
	v_lshl_add_u64 v[6:7], s[38:39], 0, v[132:133]
	v_lshl_add_u64 v[4:5], s[38:39], 0, v[128:129]
	v_lshl_add_u64 v[0:1], s[36:37], 0, v[134:135]
	s_cselect_b64 s[8:9], -1, 0
	s_cmp_lg_u32 s17, 1
	v_lshl_add_u64 v[2:3], s[36:37], 0, v[130:131]
	s_cbranch_scc1 .LBB0_1224
	s_barrier
